# row rms-norm loops (P1, P4 tail): wave sum via DPP instead of six serialized ds_bpermute steps
# speedup vs baseline: 1.0091x; 1.0091x over previous
.LBB0_108:
	global_load_dwordx4 v[52:55], v[38:39], off offset:-2048
	global_load_dwordx4 v[56:59], v[38:39], off offset:-1024
	global_load_dwordx4 v[60:63], v[38:39], off
	global_load_dwordx4 v[64:67], v[38:39], off offset:1024
	v_lshl_add_u64 v[68:69], v[20:21], 0, s[8:9]
	s_add_u32 s8, s8, 0x800
	s_addc_u32 s9, s9, 0
	v_lshl_add_u64 v[38:39], v[38:39], 0, s[6:7]
	s_cmp_lg_u32 s8, 0x10000
	s_waitcnt vmcnt(3)
	v_pk_mul_f32 v[70:71], v[54:55], v[54:55]
	v_pk_mul_f32 v[72:73], v[52:53], v[52:53]
	s_waitcnt vmcnt(2)
	v_pk_mul_f32 v[74:75], v[58:59], v[58:59]
	v_pk_mul_f32 v[76:77], v[56:57], v[56:57]
	v_pk_mov_b32 v[82:83], v[72:73], v[70:71] op_sel:[1,0]
	v_mov_b32_e32 v73, v71
	v_pk_mov_b32 v[70:71], v[76:77], v[74:75] op_sel:[1,0]
	v_mov_b32_e32 v77, v75
	s_waitcnt vmcnt(0)
	v_mul_f32_e32 v81, v67, v67
	v_mul_f32_e32 v78, v61, v61
	v_mul_f32_e32 v80, v63, v63
	v_pk_add_f32 v[72:73], v[82:83], v[72:73]
	v_pk_add_f32 v[70:71], v[70:71], v[76:77]
	v_mul_f32_e32 v51, v66, v66
	v_mul_f32_e32 v84, v64, v64
	v_mul_f32_e32 v85, v65, v65
	v_pk_fma_f32 v[74:75], v[60:61], v[60:61], v[78:79] op_sel_hi:[1,1,0]
	v_pk_fma_f32 v[78:79], v[62:63], v[62:63], v[80:81] op_sel_hi:[1,1,0]
	v_pk_add_f32 v[72:73], v[72:73], v[72:73] op_sel:[0,1] op_sel_hi:[1,0]
	v_pk_add_f32 v[70:71], v[70:71], v[70:71] op_sel:[0,1] op_sel_hi:[1,0]
	v_mov_b32_e32 v75, v51
	v_mov_b32_e32 v79, v81
	v_mov_b32_e32 v73, v84
	v_mov_b32_e32 v71, v85
	v_pk_add_f32 v[74:75], v[74:75], v[78:79]
	v_pk_add_f32 v[70:71], v[72:73], v[70:71]
	s_nop 0
	v_pk_add_f32 v[70:71], v[70:71], v[74:75]
	s_nop 0
	v_add_f32_e32 v51, v70, v71
	s_nop 1
	v_add_f32_dpp v70, v51, v51 row_shr:1 row_mask:0xf bank_mask:0xf bound_ctrl:0
	s_nop 1
	v_add_f32_dpp v70, v51, v70 row_shr:2 row_mask:0xf bank_mask:0xf bound_ctrl:0
	s_nop 1
	v_add_f32_dpp v70, v51, v70 row_shr:3 row_mask:0xf bank_mask:0xf bound_ctrl:0
	s_nop 1
	v_add_f32_dpp v70, v70, v70 row_shr:4 row_mask:0xf bank_mask:0xe
	s_nop 1
	v_add_f32_dpp v70, v70, v70 row_shr:8 row_mask:0xf bank_mask:0xc
	s_nop 1
	v_add_f32_dpp v70, v70, v70 row_bcast:15 row_mask:0xa bank_mask:0xf
	s_nop 1
	v_add_f32_dpp v70, v70, v70 row_bcast:31 row_mask:0xc bank_mask:0xf
	s_nop 1
	v_readlane_b32 s98, v70, 63
	s_nop 0
	v_mov_b32_e32 v51, s98
	v_fmamk_f32 v51, v51, 0x3a800000, v50
	v_mul_f32_e32 v70, 0x4b800000, v51
	v_cmp_gt_f32_e32 vcc, s10, v51
	s_nop 1
	v_cndmask_b32_e32 v51, v51, v70, vcc
	v_rsq_f32_e32 v51, v51
	s_nop 0
	v_mul_f32_e32 v70, 0x45800000, v51
	v_cndmask_b32_e32 v70, v51, v70, vcc
	v_pk_mul_f32 v[52:53], v[52:53], v[70:71] op_sel_hi:[1,0]
	v_pk_mul_f32 v[54:55], v[54:55], v[70:71] op_sel_hi:[1,0]
	v_pk_mul_f32 v[56:57], v[56:57], v[70:71] op_sel_hi:[1,0]
	v_pk_mul_f32 v[58:59], v[58:59], v[70:71] op_sel_hi:[1,0]
	v_pk_fma_f32 v[52:53], v[24:25], v[52:53], v[0:1]
	v_pk_mul_f32 v[60:61], v[60:61], v[70:71] op_sel_hi:[1,0]
	v_pk_mul_f32 v[62:63], v[62:63], v[70:71] op_sel_hi:[1,0]
	v_pk_mul_f32 v[64:65], v[64:65], v[70:71] op_sel_hi:[1,0]
	v_pk_mul_f32 v[66:67], v[66:67], v[70:71] op_sel_hi:[1,0]
	v_pk_fma_f32 v[54:55], v[22:23], v[54:55], v[2:3]
	v_pk_fma_f32 v[58:59], v[26:27], v[58:59], v[6:7]
	v_pk_fma_f32 v[56:57], v[28:29], v[56:57], v[4:5]
	v_cvt_pk_bf16_f32 v52, v52, v53
	v_cvt_pk_bf16_f32 v53, v54, v55
	v_pk_fma_f32 v[62:63], v[30:31], v[62:63], v[10:11]
	v_pk_fma_f32 v[60:61], v[32:33], v[60:61], v[8:9]
	v_pk_fma_f32 v[66:67], v[34:35], v[66:67], v[14:15]
	v_pk_fma_f32 v[64:65], v[36:37], v[64:65], v[12:13]
	v_cvt_pk_bf16_f32 v54, v56, v57
	v_cvt_pk_bf16_f32 v55, v58, v59
	v_cvt_pk_bf16_f32 v56, v60, v61
	v_cvt_pk_bf16_f32 v57, v62, v63
	v_cvt_pk_bf16_f32 v59, v66, v67
	s_nop 0
	v_cvt_pk_bf16_f32 v58, v64, v65
	global_store_dwordx2 v[68:69], v[52:53], off offset:-1024
	global_store_dwordx2 v[68:69], v[54:55], off offset:-512
	global_store_dwordx2 v[68:69], v[56:57], off
	global_store_dwordx2 v[68:69], v[58:59], off offset:512
	s_cbranch_scc1 .LBB0_108
	s_add_i32 s52, s52, s68
	v_lshl_add_u64 v[18:19], v[18:19], 0, s[0:1]
	s_cmpk_lt_i32 s52, 0x800
	v_lshl_add_u64 v[20:21], v[20:21], 0, s[4:5]
	s_cbranch_scc1 .LBB0_107

.LBB0_441:
	v_lshl_add_u64 v[38:39], s[86:87], 0, v[20:21]
	v_add_co_u32_e32 v40, vcc, 0x2a000000, v38
	s_nop 1
	v_addc_co_u32_e32 v41, vcc, 0, v39, vcc
	global_load_dwordx2 v[42:43], v[40:41], off
	global_load_dwordx2 v[44:45], v[40:41], off offset:512
	global_load_dwordx2 v[48:49], v[40:41], off offset:1024
	s_nop 0
	global_load_dwordx2 v[40:41], v[40:41], off offset:1536
	s_waitcnt vmcnt(3)
	v_and_b32_e32 v55, 0xffff0000, v42
	v_and_b32_e32 v57, 0xffff0000, v43
	v_lshlrev_b32_e32 v54, 16, v42
	v_lshlrev_b32_e32 v56, 16, v43
	s_waitcnt vmcnt(2)
	v_lshlrev_b32_e32 v53, 16, v45
	v_lshlrev_b32_e32 v52, 16, v44
	v_and_b32_e32 v51, 0xffff0000, v45
	v_and_b32_e32 v50, 0xffff0000, v44
	s_waitcnt vmcnt(1)
	v_and_b32_e32 v47, 0xffff0000, v48
	s_waitcnt vmcnt(0)
	v_lshlrev_b32_e32 v45, 16, v40
	v_and_b32_e32 v43, 0xffff0000, v40
	v_mul_f32_e32 v42, v57, v57
	v_mul_f32_e32 v44, v55, v55
	v_lshlrev_b32_e32 v46, 16, v48
	v_lshlrev_b32_e32 v48, 16, v49
	v_and_b32_e32 v49, 0xffff0000, v49
	v_pk_mul_f32 v[70:71], v[50:51], v[50:51]
	v_mov_b32_e32 v73, v45
	v_mul_f32_e32 v72, v47, v47
	v_pk_fma_f32 v[76:77], v[56:57], v[56:57], v[42:43] op_sel_hi:[1,1,0]
	v_pk_fma_f32 v[78:79], v[54:55], v[54:55], v[44:45] op_sel_hi:[1,1,0]
	v_lshlrev_b32_e32 v40, 16, v41
	v_and_b32_e32 v41, 0xffff0000, v41
	v_mul_f32_e32 v74, v49, v49
	v_pk_fma_f32 v[70:71], v[52:53], v[52:53], v[70:71]
	v_pk_fma_f32 v[80:81], v[46:47], v[46:47], v[72:73] op_sel_hi:[1,1,0]
	v_mov_b32_e32 v44, v78
	v_mov_b32_e32 v72, v76
	v_mul_f32_e32 v69, v43, v43
	v_mul_f32_e32 v82, v40, v40
	v_mul_f32_e32 v83, v41, v41
	v_pk_fma_f32 v[74:75], v[48:49], v[48:49], v[74:75] op_sel_hi:[1,1,0]
	v_pk_add_f32 v[76:77], v[78:79], v[76:77]
	v_pk_add_f32 v[70:71], v[70:71], v[70:71] op_sel:[0,1] op_sel_hi:[1,0]
	v_pk_mul_f32 v[72:73], v[44:45], v[72:73]
	v_mov_b32_e32 v81, v82
	v_mov_b32_e32 v75, v83
	v_mov_b32_e32 v71, v69
	v_mov_b32_e32 v77, v73
	v_pk_add_f32 v[74:75], v[80:81], v[74:75]
	v_pk_add_f32 v[70:71], v[76:77], v[70:71]
	s_nop 0
	v_pk_add_f32 v[70:71], v[70:71], v[74:75]
	s_nop 0
	v_add_f32_e32 v42, v70, v71
	s_nop 1
	v_add_f32_dpp v44, v42, v42 row_shr:1 row_mask:0xf bank_mask:0xf bound_ctrl:0
	s_nop 1
	v_add_f32_dpp v44, v42, v44 row_shr:2 row_mask:0xf bank_mask:0xf bound_ctrl:0
	s_nop 1
	v_add_f32_dpp v44, v42, v44 row_shr:3 row_mask:0xf bank_mask:0xf bound_ctrl:0
	s_nop 1
	v_add_f32_dpp v44, v44, v44 row_shr:4 row_mask:0xf bank_mask:0xe
	s_nop 1
	v_add_f32_dpp v44, v44, v44 row_shr:8 row_mask:0xf bank_mask:0xc
	s_nop 1
	v_add_f32_dpp v44, v44, v44 row_bcast:15 row_mask:0xa bank_mask:0xf
	s_nop 1
	v_add_f32_dpp v44, v44, v44 row_bcast:31 row_mask:0xc bank_mask:0xf
	s_nop 1
	v_readlane_b32 s98, v44, 63
	s_nop 0
	v_mov_b32_e32 v42, s98
	v_fmamk_f32 v42, v42, 0x3a800000, v68
	v_mul_f32_e32 v44, 0x4b800000, v42
	v_cmp_gt_f32_e32 vcc, s2, v42
	s_nop 1
	v_cndmask_b32_e32 v42, v42, v44, vcc
	v_rsq_f32_e32 v42, v42
	s_nop 0
	v_mul_f32_e32 v44, 0x45800000, v42
	v_cndmask_b32_e32 v44, v42, v44, vcc
	s_and_saveexec_b64 s[12:13], s[0:1]
	s_cbranch_execz .LBB0_440
	s_add_u32 s18, s86, s15
	s_addc_u32 s19, s87, s16
	global_store_dword v17, v44, s[18:19]
	s_branch .LBB0_440
